# a9: a7g2 + S5 phase-C state loads hoisted to loop top (one exposed latency per task instead of three)
# baseline (speedup 1.0000x reference)
; DEVI int crow(int r, int hi) { return (r & 3) + 8 * (r >> 2) + 4 * hi; }
; template <bool PHASE_C>
; DEVI void phase_s5(const Params& p, char* lds) {
;     ...
;    for (int kc = sub; kc < NCHUNK; kc += 8) {
;     const int tok0 = kc < 256 ? b * SEQL + kc * 32 : NLAT + b * CTXL + (kc - 256) * 32;
;     const bf16x8 afrag = *(const bf16x8*)(U + (size_t)(tok0 + r32) * LDP + g * 16 + hi * 8);
;     f32x4 y0 = {0, 0, 0, 0}, y1 = {0, 0, 0, 0};
; #pragma unroll
;     for (int d = 0; d < 2; ++d) {
;       const int j = kc < 256 ? (d ? 8 + 255 - kc : 8 + kc) : (d ? 7 - (kc - 256) : (kc - 256));
; #pragma unroll
;       for (int nt = 0; nt < 4; ++nt) {
;         f32x16 acc = {};
;         acc = __builtin_amdgcn_mfma_f32_32x32x16_bf16(afrag, bb[d][nt], acc, 0, 0, 0);
; #pragma unroll
;         for (int i = 0; i < 16; ++i) wl[crow(i, hi) * 132 + nt * 32 + r32] = acc[i];
;       }
;       asm volatile("s_waitcnt lgkmcnt(0)" ::: "memory");
;       const float ar = arr[d], ai = aii[d];
;       float hr = 0.f, him = 0.f;
;       float* sp = S + ((size_t)((b * 2 + d) * 64 + g) * NCHUNK + j) * 128;
;       if (PHASE_C) { hr = sp[lane]; him = sp[64 + lane]; }
;       float bur[32], bui[32];
; #pragma unroll
;       for (int s = 0; s < 32; ++s) { bur[s] = wl[s * 132 + lane]; bui[s] = wl[s * 132 + 64 + lane]; }
; #pragma unroll
;       for (int s = 0; s < 32; ++s) {
;         const int t = d ? 31 - s : s;
;         const float nr = ar * hr - ai * him + bur[t];
;         const float ni = ar * him + ai * hr + bui[t];
;         hr = nr; him = ni;
;         if (PHASE_C) { bur[t] = hr; bui[t] = him; }
;       }
;       if (PHASE_C) {
; #pragma unroll
;         for (int s = 0; s < 32; ++s) { wl[s * 132 + lane] = bur[s]; wl[s * 132 + 64 + lane] = bui[s]; }
;       }
;       if (!PHASE_C) { sp[lane] = hr; sp[64 + lane] = him; }
.LBB0_467:
	v_add_u32_e32 v185, -8, v175
	v_cmp_gt_u32_e32 vcc, s26, v185
	v_add_u32_e32 v194, 0x400, v167
	v_add_u32_e32 v195, 0x1000, v167
	v_cndmask_b32_e32 v180, v173, v174, vcc
	v_add3_u32 v0, v161, v180, v176
	v_mad_i64_i32 v[0:1], s[4:5], v0, s27, v[148:149]
	global_load_dwordx4 v[134:137], v[0:1], off
	v_add_u32_e32 v196, 0x1400, v167
	v_add_u32_e32 v197, 0x2000, v167
	v_add_u32_e32 v198, 0x2400, v167
	v_add_u32_e32 v199, 0x3000, v167
	v_add_u32_e32 v205, 0x3200, v167
	v_add_u32_e32 v200, 0x3400, v167
	v_add_u32_e32 v206, 0x3600, v167
	v_add_u32_e32 v32, 0xfffffef8, v175
	v_cndmask_b32_e32 v138, v32, v175, vcc
	v_lshl_add_u64 v[250:251], v[154:155], 0, v[138:139]
	v_lshlrev_b64 v[250:251], 9, v[250:251]
	v_lshl_add_u64 v[250:251], v[144:145], 0, v[250:251]
	global_load_dword v246, v[250:251], off offset:256
	global_load_dword v247, v[250:251], off
	global_load_dword v248, v[156:157], off offset:256
	global_load_dword v249, v[156:157], off
	v_add_u32_e32 v201, 0x1200, v167
	v_add_u32_e32 v202, 0x1600, v167
	v_add_u32_e32 v203, 0x2800, v167
	v_add_u32_e32 v204, 0x3800, v167
	v_add_u32_e32 v177, 32, v163
	v_add_u32_e32 v178, 48, v163
	v_add_u32_e32 v179, 64, v163
	v_add_u32_e32 v181, 0x50, v163
	v_add_u32_e32 v182, 0x60, v163
	v_add_u32_e32 v183, 0x70, v163
	v_add_u32_e32 v184, 0x80, v163
	v_add_u32_e32 v186, 0x90, v163
	v_add_u32_e32 v187, 0xa0, v163
	v_add_u32_e32 v188, 0xb0, v163
	v_add_u32_e32 v189, 0xc0, v163
	v_add_u32_e32 v190, 0xd0, v163
	v_add_u32_e32 v191, 0xe0, v163
	v_add_u32_e32 v192, 0xf0, v163
	v_add_u32_e32 v193, 16, v163
	v_cmp_lt_u32_e32 vcc, s70, v185
	s_or_b64 s[68:69], vcc, s[68:69]
	v_add_u32_e32 v175, 8, v175
	s_waitcnt vmcnt(4)
	v_mfma_f32_32x32x16_bf16 v[0:15], v[134:137], v[42:45], 0
	v_mfma_f32_32x32x16_bf16 v[16:31], v[134:137], v[50:53], 0
	s_nop 11
	ds_write2_b32 v167, v0, v16 offset1:32
	ds_write2_b32 v167, v1, v17 offset0:132 offset1:164
	ds_write2_b32 v194, v2, v18 offset0:8 offset1:40
	ds_write2_b32 v194, v3, v19 offset0:140 offset1:172
	ds_write2_b32 v195, v4, v20 offset0:32 offset1:64
	ds_write2_b32 v195, v5, v21 offset0:164 offset1:196
	ds_write2_b32 v196, v6, v22 offset0:40 offset1:72
	ds_write2_b32 v196, v7, v23 offset0:172 offset1:204
	ds_write2_b32 v197, v8, v24 offset0:64 offset1:96
	ds_write2_b32 v197, v9, v25 offset0:196 offset1:228
	ds_write2_b32 v198, v10, v26 offset0:72 offset1:104
	ds_write2_b32 v198, v11, v27 offset0:204 offset1:236
	ds_write2_b32 v199, v12, v28 offset0:96 offset1:128
	ds_write2_b32 v205, v13, v29 offset0:100 offset1:132
	ds_write2_b32 v200, v14, v30 offset0:104 offset1:136
	ds_write2_b32 v206, v15, v31 offset0:108 offset1:140
	v_mfma_f32_32x32x16_bf16 v[0:15], v[134:137], v[58:61], 0
	v_mfma_f32_32x32x16_bf16 v[16:31], v[134:137], v[66:69], 0
	s_nop 11
	ds_write2_b32 v167, v0, v16 offset0:64 offset1:96
	ds_write2_b32 v167, v1, v17 offset0:196 offset1:228
	ds_write2_b32 v194, v2, v18 offset0:72 offset1:104
	ds_write2_b32 v194, v3, v19 offset0:204 offset1:236
	ds_write2_b32 v195, v4, v20 offset0:96 offset1:128
	ds_write2_b32 v201, v5, v21 offset0:100 offset1:132
	ds_write2_b32 v196, v6, v22 offset0:104 offset1:136
	ds_write2_b32 v202, v7, v23 offset0:108 offset1:140
	ds_write2_b32 v197, v8, v24 offset0:128 offset1:160
	ds_write2_b32 v198, v9, v25 offset0:4 offset1:36
	ds_write2_b32 v198, v10, v26 offset0:136 offset1:168
	ds_write2_b32 v203, v11, v27 offset0:12 offset1:44
	ds_write2_b32 v199, v12, v28 offset0:160 offset1:192
	ds_write2_b32 v200, v13, v29 offset0:36 offset1:68
	ds_write2_b32 v200, v14, v30 offset0:168 offset1:200
	ds_write2_b32 v204, v15, v31 offset0:44 offset1:76
	s_waitcnt lgkmcnt(0)
	ds_read2st64_b32 v[0:1], v163 offset1:1
	ds_read2_b32 v[2:3], v163 offset0:132 offset1:196
	ds_read2st64_b32 v[4:5], v177 offset0:4 offset1:5
	ds_read2st64_b32 v[6:7], v163 offset0:33 offset1:34
	ds_read2st64_b32 v[8:9], v178 offset0:6 offset1:7
	ds_read2st64_b32 v[10:11], v177 offset0:37 offset1:38
	ds_read2st64_b32 v[12:13], v178 offset0:39 offset1:40
	ds_read2st64_b32 v[14:15], v179 offset0:8 offset1:9
	ds_read2st64_b32 v[16:17], v179 offset0:41 offset1:42
	ds_read2st64_b32 v[18:19], v181 offset0:10 offset1:11
	ds_read2st64_b32 v[20:21], v181 offset0:43 offset1:44
	ds_read2st64_b32 v[22:23], v182 offset0:12 offset1:13
	ds_read2st64_b32 v[24:25], v182 offset0:45 offset1:46
	ds_read2st64_b32 v[26:27], v183 offset0:14 offset1:15
	s_waitcnt vmcnt(3)
	v_mul_f32_e32 v30, v169, v246
	v_mul_f32_e32 v28, v168, v246
	s_waitcnt vmcnt(2)
	v_fmac_f32_e32 v28, v169, v247
	v_fma_f32 v30, v168, v247, -v30
	s_waitcnt lgkmcnt(13)
	v_add_f32_e32 v28, v28, v1
	v_add_f32_e32 v29, v0, v30
	v_mul_f32_e32 v30, v169, v28
	ds_write2st64_b32 v163, v29, v28 offset1:1
	v_fma_f32 v30, v168, v29, -v30
	v_mul_f32_e32 v29, v169, v29
	v_fmac_f32_e32 v29, v168, v28
	s_waitcnt lgkmcnt(13)
	v_add_f32_e32 v29, v3, v29
	v_add_f32_e32 v28, v2, v30
	v_mul_f32_e32 v30, v169, v29
	ds_write2_b32 v163, v28, v29 offset0:132 offset1:196
	v_fma_f32 v30, v168, v28, -v30
	v_mul_f32_e32 v28, v169, v28
	v_fmac_f32_e32 v28, v168, v29
	s_waitcnt lgkmcnt(13)
	v_add_f32_e32 v28, v5, v28
	v_add_f32_e32 v29, v4, v30
	v_mul_f32_e32 v30, v169, v28
	ds_write2st64_b32 v177, v29, v28 offset0:4 offset1:5
	v_fma_f32 v30, v168, v29, -v30
	v_mul_f32_e32 v29, v169, v29
	v_fmac_f32_e32 v29, v168, v28
	s_waitcnt lgkmcnt(12)
	v_add_f32_e32 v29, v9, v29
	v_add_f32_e32 v28, v8, v30
	v_mul_f32_e32 v30, v169, v29
	ds_write2st64_b32 v178, v28, v29 offset0:6 offset1:7
	v_fma_f32 v30, v168, v28, -v30
	v_mul_f32_e32 v28, v169, v28
	v_fmac_f32_e32 v28, v168, v29
	s_waitcnt lgkmcnt(10)
; template <bool PHASE_C>
; DEVI void phase_s5(const Params& p, char* lds) {
;     ...
;       float bur[32], bui[32];
; #pragma unroll
;       for (int s = 0; s < 32; ++s) { bur[s] = wl[s * 132 + lane]; bui[s] = wl[s * 132 + 64 + lane]; }
; #pragma unroll
;       for (int s = 0; s < 32; ++s) {
;         const int t = d ? 31 - s : s;
;         const float nr = ar * hr - ai * him + bur[t];
;         const float ni = ar * him + ai * hr + bui[t];
;         hr = nr; him = ni;
;         if (PHASE_C) { bur[t] = hr; bui[t] = him; }
;       }
;       if (PHASE_C) {
; #pragma unroll
;         for (int s = 0; s < 32; ++s) { wl[s * 132 + lane] = bur[s]; wl[s * 132 + 64 + lane] = bui[s]; }
	v_add_f32_e32 v28, v15, v28
	v_add_f32_e32 v29, v14, v30
	v_mul_f32_e32 v30, v169, v28
	ds_write2st64_b32 v179, v29, v28 offset0:8 offset1:9
	v_fma_f32 v30, v168, v29, -v30
	v_mul_f32_e32 v29, v169, v29
	v_fmac_f32_e32 v29, v168, v28
	s_waitcnt lgkmcnt(9)
	v_add_f32_e32 v29, v19, v29
	v_add_f32_e32 v28, v18, v30
	v_mul_f32_e32 v30, v169, v29
	ds_write2st64_b32 v181, v28, v29 offset0:10 offset1:11
	v_fma_f32 v30, v168, v28, -v30
	v_mul_f32_e32 v28, v169, v28
	v_fmac_f32_e32 v28, v168, v29
	s_waitcnt lgkmcnt(8)
	v_add_f32_e32 v28, v23, v28
	v_add_f32_e32 v29, v22, v30
	v_mul_f32_e32 v30, v169, v28
	ds_write2st64_b32 v182, v29, v28 offset0:12 offset1:13
	v_fma_f32 v30, v168, v29, -v30
	v_mul_f32_e32 v29, v169, v29
	ds_read2st64_b32 v[2:3], v184 offset0:16 offset1:17
	ds_read2st64_b32 v[4:5], v184 offset0:49 offset1:50
	v_fmac_f32_e32 v29, v168, v28
	s_waitcnt lgkmcnt(9)
	v_add_f32_e32 v29, v27, v29
	v_add_f32_e32 v28, v26, v30
	v_mul_f32_e32 v30, v169, v29
	ds_write2st64_b32 v183, v28, v29 offset0:14 offset1:15
	v_fma_f32 v30, v168, v28, -v30
	v_mul_f32_e32 v28, v169, v28
	ds_read2st64_b32 v[8:9], v186 offset0:18 offset1:19
	ds_read2st64_b32 v[14:15], v186 offset0:51 offset1:52
	v_fmac_f32_e32 v28, v168, v29
	s_waitcnt lgkmcnt(4)
	v_add_f32_e32 v28, v3, v28
	v_add_f32_e32 v29, v2, v30
	v_mul_f32_e32 v30, v169, v28
	ds_write2st64_b32 v184, v29, v28 offset0:16 offset1:17
	v_fma_f32 v30, v168, v29, -v30
	v_mul_f32_e32 v29, v169, v29
	ds_read2st64_b32 v[18:19], v187 offset0:20 offset1:21
	ds_read2st64_b32 v[22:23], v187 offset0:53 offset1:54
	v_fmac_f32_e32 v29, v168, v28
	s_waitcnt lgkmcnt(4)
	v_add_f32_e32 v29, v9, v29
	v_add_f32_e32 v28, v8, v30
	v_mul_f32_e32 v30, v169, v29
	ds_write2st64_b32 v186, v28, v29 offset0:18 offset1:19
	v_fma_f32 v30, v168, v28, -v30
	v_mul_f32_e32 v28, v169, v28
	ds_read2st64_b32 v[26:27], v188 offset0:22 offset1:23
	ds_read2st64_b32 v[2:3], v188 offset0:55 offset1:56
	v_fmac_f32_e32 v28, v168, v29
	s_waitcnt lgkmcnt(4)
	v_add_f32_e32 v28, v19, v28
	v_add_f32_e32 v29, v18, v30
	v_mul_f32_e32 v30, v169, v28
	ds_write2st64_b32 v187, v29, v28 offset0:20 offset1:21
	v_fma_f32 v30, v168, v29, -v30
	v_mul_f32_e32 v29, v169, v29
	ds_read2st64_b32 v[8:9], v189 offset0:24 offset1:25
	ds_read2st64_b32 v[18:19], v189 offset0:57 offset1:58
	v_fmac_f32_e32 v29, v168, v28
	s_waitcnt lgkmcnt(4)
	v_add_f32_e32 v29, v27, v29
	v_add_f32_e32 v28, v26, v30
	v_mul_f32_e32 v30, v169, v29
	ds_write2st64_b32 v188, v28, v29 offset0:22 offset1:23
	v_fma_f32 v30, v168, v28, -v30
	v_mul_f32_e32 v28, v169, v28
	ds_read2st64_b32 v[26:27], v190 offset0:26 offset1:27
	v_fmac_f32_e32 v28, v168, v29
	s_waitcnt lgkmcnt(3)
	v_add_f32_e32 v28, v9, v28
	v_add_f32_e32 v29, v8, v30
	v_mul_f32_e32 v30, v169, v28
	ds_write2st64_b32 v189, v29, v28 offset0:24 offset1:25
	v_fma_f32 v30, v168, v29, -v30
	v_mul_f32_e32 v29, v169, v29
	v_fmac_f32_e32 v29, v168, v28
	ds_read2st64_b32 v[8:9], v190 offset0:59 offset1:60
	s_waitcnt lgkmcnt(2)
	v_add_f32_e32 v28, v26, v30
	v_add_f32_e32 v29, v27, v29
	ds_read2st64_b32 v[26:27], v191 offset0:28 offset1:29
	v_mul_f32_e32 v30, v169, v29
	ds_write2st64_b32 v190, v28, v29 offset0:26 offset1:27
	v_fma_f32 v30, v168, v28, -v30
	v_mul_f32_e32 v28, v169, v28
	v_fmac_f32_e32 v28, v168, v29
	s_waitcnt lgkmcnt(1)
	v_add_f32_e32 v29, v26, v30
	v_add_f32_e32 v28, v27, v28
	ds_read2st64_b32 v[26:27], v192 offset0:30 offset1:31
	v_mul_f32_e32 v30, v169, v28
	ds_write2st64_b32 v191, v29, v28 offset0:28 offset1:29
	v_fma_f32 v30, v168, v29, -v30
	v_mul_f32_e32 v29, v169, v29
	v_fmac_f32_e32 v29, v168, v28
	s_waitcnt lgkmcnt(1)
	v_add_f32_e32 v29, v27, v29
	v_add_f32_e32 v28, v26, v30
	v_mul_f32_e32 v30, v169, v29
	ds_write2st64_b32 v192, v28, v29 offset0:30 offset1:31
	v_fma_f32 v30, v168, v28, -v30
	v_mul_f32_e32 v28, v169, v28
	v_fmac_f32_e32 v28, v168, v29
	v_add_f32_e32 v29, v6, v30
	v_add_f32_e32 v28, v7, v28
	ds_read2st64_b32 v[6:7], v193 offset0:35 offset1:36
	v_mul_f32_e32 v30, v169, v28
	ds_write2st64_b32 v163, v29, v28 offset0:33 offset1:34
	v_fma_f32 v30, v168, v29, -v30
	v_mul_f32_e32 v29, v169, v29
	v_fmac_f32_e32 v29, v168, v28
	s_waitcnt lgkmcnt(1)
	v_add_f32_e32 v29, v7, v29
	v_add_f32_e32 v28, v6, v30
	v_mul_f32_e32 v30, v169, v29
	ds_write2st64_b32 v193, v28, v29 offset0:35 offset1:36
	v_fma_f32 v30, v168, v28, -v30
	v_mul_f32_e32 v28, v169, v28
	v_fmac_f32_e32 v28, v168, v29
	v_add_f32_e32 v10, v10, v30
	v_add_f32_e32 v11, v11, v28
	v_mul_f32_e32 v28, v169, v11
	v_mul_f32_e32 v29, v169, v10
	ds_write2st64_b32 v177, v10, v11 offset0:37 offset1:38
	v_fma_f32 v10, v168, v10, -v28
	v_fmac_f32_e32 v29, v168, v11
	v_add_f32_e32 v10, v12, v10
	v_add_f32_e32 v11, v13, v29
	v_mul_f32_e32 v12, v169, v11
	v_mul_f32_e32 v13, v169, v10
	ds_write2st64_b32 v178, v10, v11 offset0:39 offset1:40
	v_fma_f32 v10, v168, v10, -v12
	v_fmac_f32_e32 v13, v168, v11
	v_add_f32_e32 v10, v16, v10
	v_add_f32_e32 v11, v17, v13
	v_mul_f32_e32 v12, v169, v11
	v_mul_f32_e32 v13, v169, v10
	ds_write2st64_b32 v179, v10, v11 offset0:41 offset1:42
	v_fma_f32 v10, v168, v10, -v12
	v_fmac_f32_e32 v13, v168, v11
	v_add_f32_e32 v10, v20, v10
	v_add_f32_e32 v11, v21, v13
	ds_read2st64_b32 v[0:1], v183 offset0:47 offset1:48
	v_mul_f32_e32 v12, v169, v11
	v_mul_f32_e32 v13, v169, v10
	ds_write2st64_b32 v181, v10, v11 offset0:43 offset1:44
	v_fma_f32 v10, v168, v10, -v12
	v_fmac_f32_e32 v13, v168, v11
	v_add_f32_e32 v10, v24, v10
	v_add_f32_e32 v11, v25, v13
	v_mul_f32_e32 v12, v169, v11
	v_mul_f32_e32 v13, v169, v10
	ds_write2st64_b32 v182, v10, v11 offset0:45 offset1:46
	v_fma_f32 v10, v168, v10, -v12
	v_fmac_f32_e32 v13, v168, v11
	s_waitcnt lgkmcnt(2)
; template <bool PHASE_C>
; DEVI void phase_s5(const Params& p, char* lds) {
;     ...
;     for (int d = 0; d < 2; ++d) {
;       const int j = kc < 256 ? (d ? 8 + 255 - kc : 8 + kc) : (d ? 7 - (kc - 256) : (kc - 256));
; #pragma unroll
;       for (int nt = 0; nt < 4; ++nt) {
;         f32x16 acc = {};
;         acc = __builtin_amdgcn_mfma_f32_32x32x16_bf16(afrag, bb[d][nt], acc, 0, 0, 0);
; #pragma unroll
;         for (int i = 0; i < 16; ++i) wl[crow(i, hi) * 132 + nt * 32 + r32] = acc[i];
;       }
;       asm volatile("s_waitcnt lgkmcnt(0)" ::: "memory");
;       const float ar = arr[d], ai = aii[d];
;       float hr = 0.f, him = 0.f;
;       float* sp = S + ((size_t)((b * 2 + d) * 64 + g) * NCHUNK + j) * 128;
;       if (PHASE_C) { hr = sp[lane]; him = sp[64 + lane]; }
;       float bur[32], bui[32];
; #pragma unroll
;       for (int s = 0; s < 32; ++s) { bur[s] = wl[s * 132 + lane]; bui[s] = wl[s * 132 + 64 + lane]; }
; #pragma unroll
;       for (int s = 0; s < 32; ++s) {
;         const int t = d ? 31 - s : s;
;         const float nr = ar * hr - ai * him + bur[t];
;         const float ni = ar * him + ai * hr + bui[t];
;         hr = nr; him = ni;
;         if (PHASE_C) { bur[t] = hr; bui[t] = him; }
;       }
;       if (PHASE_C) {
; #pragma unroll
;         for (int s = 0; s < 32; ++s) { wl[s * 132 + lane] = bur[s]; wl[s * 132 + 64 + lane] = bui[s]; }
;       }
;       if (!PHASE_C) { sp[lane] = hr; sp[64 + lane] = him; }
;       if (PHASE_C) {
;         asm volatile("s_waitcnt lgkmcnt(0)" ::: "memory");
; #pragma unroll
;         for (int ks = 0; ks < 4; ++ks) {
;           const bf16x8 cf = cm[d][ks];
;           const float* a0p = wl + (lane & 15) * 132 + ks * 32 + (lane >> 4) * 8;
;           const f32x4 a00 = *(const f32x4*)a0p, a01 = *(const f32x4*)(a0p + 4);
;           const f32x4 a10 = *(const f32x4*)(a0p + 16 * 132), a11 = *(const f32x4*)(a0p + 16 * 132 + 4);
;           u32x4 w0 = {cvtpk(a00[0], a00[1]), cvtpk(a00[2], a00[3]), cvtpk(a01[0], a01[1]), cvtpk(a01[2], a01[3])};
;           u32x4 w1 = {cvtpk(a10[0], a10[1]), cvtpk(a10[2], a10[3]), cvtpk(a11[0], a11[1]), cvtpk(a11[2], a11[3])};
;           y0 = __builtin_amdgcn_mfma_f32_16x16x32_bf16(*(bf16x8*)&w0, cf, y0, 0, 0, 0);
;           y1 = __builtin_amdgcn_mfma_f32_16x16x32_bf16(*(bf16x8*)&w1, cf, y1, 0, 0, 0);
;         }
	v_add_f32_e32 v0, v0, v10
	v_add_f32_e32 v1, v1, v13
	v_mul_f32_e32 v10, v169, v1
	v_mul_f32_e32 v11, v169, v0
	ds_write2st64_b32 v183, v0, v1 offset0:47 offset1:48
	v_fma_f32 v0, v168, v0, -v10
	v_fmac_f32_e32 v11, v168, v1
	v_add_f32_e32 v0, v4, v0
	v_add_f32_e32 v1, v5, v11
	v_mul_f32_e32 v4, v169, v1
	v_mul_f32_e32 v5, v169, v0
	ds_write2st64_b32 v184, v0, v1 offset0:49 offset1:50
	v_fma_f32 v0, v168, v0, -v4
	v_fmac_f32_e32 v5, v168, v1
	v_add_f32_e32 v0, v14, v0
	v_add_f32_e32 v1, v15, v5
	v_mul_f32_e32 v4, v169, v1
	v_mul_f32_e32 v5, v169, v0
	ds_write2st64_b32 v186, v0, v1 offset0:51 offset1:52
	v_fma_f32 v0, v168, v0, -v4
	v_fmac_f32_e32 v5, v168, v1
	v_add_f32_e32 v0, v22, v0
	v_add_f32_e32 v1, v23, v5
	v_mul_f32_e32 v4, v169, v1
	v_mul_f32_e32 v5, v169, v0
	ds_write2st64_b32 v187, v0, v1 offset0:53 offset1:54
	v_fma_f32 v0, v168, v0, -v4
	v_fmac_f32_e32 v5, v168, v1
	v_add_f32_e32 v0, v2, v0
	v_add_f32_e32 v1, v3, v5
	v_mul_f32_e32 v2, v169, v1
	v_mul_f32_e32 v3, v169, v0
	ds_write2st64_b32 v188, v0, v1 offset0:55 offset1:56
	v_fma_f32 v0, v168, v0, -v2
	v_fmac_f32_e32 v3, v168, v1
	v_add_f32_e32 v0, v18, v0
	v_add_f32_e32 v1, v19, v3
	ds_read2st64_b32 v[26:27], v191 offset0:61 offset1:62
	v_mul_f32_e32 v2, v169, v1
	v_mul_f32_e32 v3, v169, v0
	ds_write2st64_b32 v189, v0, v1 offset0:57 offset1:58
	v_fma_f32 v0, v168, v0, -v2
	v_fmac_f32_e32 v3, v168, v1
	v_add_f32_e32 v0, v8, v0
	v_add_f32_e32 v1, v9, v3
	ds_read2st64_b32 v[6:7], v192 offset0:63 offset1:64
	v_mul_f32_e32 v2, v169, v1
	v_mul_f32_e32 v3, v169, v0
	ds_write2st64_b32 v190, v0, v1 offset0:59 offset1:60
	v_fma_f32 v0, v168, v0, -v2
	v_fmac_f32_e32 v3, v168, v1
	s_waitcnt lgkmcnt(3)
	v_add_f32_e32 v0, v26, v0
	v_add_f32_e32 v1, v27, v3
	v_mul_f32_e32 v2, v169, v1
	v_mul_f32_e32 v3, v169, v0
	ds_write2st64_b32 v191, v0, v1 offset0:61 offset1:62
	v_fma_f32 v0, v168, v0, -v2
	v_fmac_f32_e32 v3, v168, v1
	s_waitcnt lgkmcnt(2)
	v_add_f32_e32 v0, v6, v0
	v_add_f32_e32 v1, v7, v3
	ds_write2st64_b32 v192, v0, v1 offset0:63 offset1:64
	v_mfma_f32_32x32x16_bf16 v[0:15], v[134:137], v[74:77], 0
	s_waitcnt lgkmcnt(0)
	ds_read_b128 v[208:211], v165
	ds_read_b128 v[212:215], v165 offset:16
	ds_read_b128 v[216:219], v165 offset:8448
	ds_read_b128 v[220:223], v165 offset:8464
	ds_read_b128 v[224:227], v165 offset:128
	ds_read_b128 v[228:231], v165 offset:144
	ds_read_b128 v[232:235], v165 offset:8576
	ds_read_b128 v[236:239], v165 offset:8592
	ds_read_b128 v[240:243], v165 offset:256
	ds_read_b128 v[126:129], v165 offset:272
	ds_read_b128 v[130:133], v165 offset:8704
	ds_read_b128 v[122:125], v165 offset:8720
	ds_read_b128 v[118:121], v165 offset:384
	ds_read_b128 v[114:117], v165 offset:400
	ds_read_b128 v[110:113], v165 offset:8832
	ds_read_b128 v[106:109], v165 offset:8848
	s_waitcnt lgkmcnt(0)
	v_mfma_f32_32x32x16_bf16 v[26:41], v[134:137], v[78:81], 0
	s_nop 11
	ds_write2_b32 v205, v13, v39 offset0:100 offset1:132
	ds_write2_b32 v206, v15, v41 offset0:108 offset1:140
	ds_write2_b32 v167, v0, v26 offset1:32
	ds_write2_b32 v167, v1, v27 offset0:132 offset1:164
	ds_write2_b32 v194, v2, v28 offset0:8 offset1:40
	ds_write2_b32 v194, v3, v29 offset0:140 offset1:172
	ds_write2_b32 v195, v4, v30 offset0:32 offset1:64
	ds_write2_b32 v195, v5, v31 offset0:164 offset1:196
	ds_write2_b32 v196, v6, v32 offset0:40 offset1:72
	v_mfma_f32_32x32x16_bf16 v[16:31], v[134:137], v[86:89], 0
	ds_write2_b32 v196, v7, v33 offset0:172 offset1:204
	ds_write2_b32 v197, v8, v34 offset0:64 offset1:96
	ds_write2_b32 v197, v9, v35 offset0:196 offset1:228
	ds_write2_b32 v198, v10, v36 offset0:72 offset1:104
	ds_write2_b32 v198, v11, v37 offset0:204 offset1:236
	ds_write2_b32 v199, v12, v38 offset0:96 offset1:128
	ds_write2_b32 v200, v14, v40 offset0:104 offset1:136
	v_mfma_f32_32x32x16_bf16 v[0:15], v[134:137], v[94:97], 0
	s_nop 11
	ds_write2_b32 v194, v18, v2 offset0:72 offset1:104
	ds_write2_b32 v194, v19, v3 offset0:204 offset1:236
	ds_write2_b32 v195, v20, v4 offset0:96 offset1:128
	ds_write2_b32 v201, v21, v5 offset0:100 offset1:132
	ds_write2_b32 v196, v22, v6 offset0:104 offset1:136
	ds_write2_b32 v202, v23, v7 offset0:108 offset1:140
	ds_write2_b32 v197, v24, v8 offset0:128 offset1:160
	ds_write2_b32 v198, v25, v9 offset0:4 offset1:36
	ds_write2_b32 v198, v26, v10 offset0:136 offset1:168
	ds_write2_b32 v203, v27, v11 offset0:12 offset1:44
	ds_write2_b32 v199, v28, v12 offset0:160 offset1:192
	ds_write2_b32 v200, v29, v13 offset0:36 offset1:68
	ds_write2_b32 v200, v30, v14 offset0:168 offset1:200
	ds_write2_b32 v204, v31, v15 offset0:44 offset1:76
	ds_write2_b32 v167, v16, v0 offset0:64 offset1:96
	ds_write2_b32 v167, v17, v1 offset0:196 offset1:228
	s_waitcnt lgkmcnt(14)
	v_cvt_pk_bf16_f32 v16, v208, v209
	v_cvt_pk_bf16_f32 v17, v210, v211
	v_cvt_pk_bf16_f32 v18, v212, v213
	v_cvt_pk_bf16_f32 v19, v214, v215
	v_cvt_pk_bf16_f32 v12, v216, v217
	v_cvt_pk_bf16_f32 v13, v218, v219
	v_cvt_pk_bf16_f32 v14, v220, v221
	v_cvt_pk_bf16_f32 v15, v222, v223
	v_cvt_pk_bf16_f32 v8, v224, v225
	s_nop 0
	v_mfma_f32_16x16x32_bf16 v[16:19], v[16:19], v[46:49], 0
	v_cvt_pk_bf16_f32 v9, v226, v227
	v_cvt_pk_bf16_f32 v10, v228, v229
	v_cvt_pk_bf16_f32 v11, v230, v231
	v_mfma_f32_16x16x32_bf16 v[12:15], v[12:15], v[46:49], 0
	v_cvt_pk_bf16_f32 v4, v232, v233
	v_cvt_pk_bf16_f32 v5, v234, v235
	v_cvt_pk_bf16_f32 v6, v236, v237
	v_cvt_pk_bf16_f32 v7, v238, v239
	v_mfma_f32_16x16x32_bf16 v[8:11], v[8:11], v[54:57], v[16:19]
	s_waitcnt lgkmcnt(0)
; DEVI unsigned cvtpk(float lo, float hi) { unsigned r; asm("v_cvt_pk_bf16_f32 %0, %1, %2" : "=v"(r) : "v"(lo), "v"(hi)); return r; }
; template <bool PHASE_C>
; DEVI void phase_s5(const Params& p, char* lds) {
;     ...
;       const float ar = arr[d], ai = aii[d];
;       float hr = 0.f, him = 0.f;
;       float* sp = S + ((size_t)((b * 2 + d) * 64 + g) * NCHUNK + j) * 128;
;       if (PHASE_C) { hr = sp[lane]; him = sp[64 + lane]; }
;       float bur[32], bui[32];
; #pragma unroll
;       for (int s = 0; s < 32; ++s) { bur[s] = wl[s * 132 + lane]; bui[s] = wl[s * 132 + 64 + lane]; }
; #pragma unroll
;       for (int s = 0; s < 32; ++s) {
;         const int t = d ? 31 - s : s;
;         const float nr = ar * hr - ai * him + bur[t];
;         const float ni = ar * him + ai * hr + bui[t];
;         hr = nr; him = ni;
;         if (PHASE_C) { bur[t] = hr; bui[t] = him; }
;       }
;       if (PHASE_C) {
; #pragma unroll
;         for (int s = 0; s < 32; ++s) { wl[s * 132 + lane] = bur[s]; wl[s * 132 + 64 + lane] = bui[s]; }
;       }
;       if (!PHASE_C) { sp[lane] = hr; sp[64 + lane] = him; }
;       if (PHASE_C) {
;         asm volatile("s_waitcnt lgkmcnt(0)" ::: "memory");
; #pragma unroll
;         for (int ks = 0; ks < 4; ++ks) {
;           const bf16x8 cf = cm[d][ks];
;           const float* a0p = wl + (lane & 15) * 132 + ks * 32 + (lane >> 4) * 8;
;           const f32x4 a00 = *(const f32x4*)a0p, a01 = *(const f32x4*)(a0p + 4);
;           const f32x4 a10 = *(const f32x4*)(a0p + 16 * 132), a11 = *(const f32x4*)(a0p + 16 * 132 + 4);
;           u32x4 w0 = {cvtpk(a00[0], a00[1]), cvtpk(a00[2], a00[3]), cvtpk(a01[0], a01[1]), cvtpk(a01[2], a01[3])};
;           u32x4 w1 = {cvtpk(a10[0], a10[1]), cvtpk(a10[2], a10[3]), cvtpk(a11[0], a11[1]), cvtpk(a11[2], a11[3])};
;           y0 = __builtin_amdgcn_mfma_f32_16x16x32_bf16(*(bf16x8*)&w0, cf, y0, 0, 0, 0);
;           y1 = __builtin_amdgcn_mfma_f32_16x16x32_bf16(*(bf16x8*)&w1, cf, y1, 0, 0, 0);
;         }
;         asm volatile("s_waitcnt lgkmcnt(0)" ::: "memory");
;       }
;     }
;     if (PHASE_C) {
;       const int c = lane & 15, ch = g * 16 + c;
;       float u0[4], u1[4];
; #pragma unroll
;       for (int r = 0; r < 4; ++r) {
;         const int t0 = (lane >> 4) * 4 + r;
;         u0[r] = bf2f(U[(size_t)(tok0 + t0) * LDP + ch]); u1[r] = bf2f(U[(size_t)(tok0 + 16 + t0) * LDP + ch]);
	v_cvt_pk_bf16_f32 v2, v126, v127
	v_cvt_pk_bf16_f32 v3, v128, v129
	v_mfma_f32_16x16x32_bf16 v[4:7], v[4:7], v[54:57], v[12:15]
	v_cvt_pk_bf16_f32 v22, v122, v123
	v_cvt_pk_bf16_f32 v0, v240, v241
	v_cvt_pk_bf16_f32 v1, v242, v243
	v_cvt_pk_bf16_f32 v20, v130, v131
	v_cvt_pk_bf16_f32 v21, v132, v133
	v_cvt_pk_bf16_f32 v23, v124, v125
	v_cvt_pk_bf16_f32 v24, v118, v119
	v_cvt_pk_bf16_f32 v25, v120, v121
	s_nop 0
	v_mfma_f32_16x16x32_bf16 v[8:11], v[0:3], v[62:65], v[8:11]
	v_cvt_pk_bf16_f32 v26, v114, v115
	v_cvt_pk_bf16_f32 v27, v116, v117
	ds_read2st64_b32 v[0:1], v163 offset1:1
	v_mfma_f32_16x16x32_bf16 v[2:5], v[20:23], v[62:65], v[4:7]
	v_add3_u32 v30, v166, v180, v176
	v_mad_i64_i32 v[126:127], s[4:5], v30, s27, v[150:151]
	v_mfma_f32_16x16x32_bf16 v[12:15], v[24:27], v[70:73], v[8:11]
	ds_read2st64_b32 v[6:7], v192 offset0:63 offset1:64
	s_nop 1
	ds_read2st64_b32 v[8:9], v191 offset0:61 offset1:62
	v_add_u32_e32 v134, 16, v30
	v_add_u32_e32 v133, 1, v30
	v_add_u32_e32 v132, 17, v30
	v_add_u32_e32 v131, 2, v30
	v_add_u32_e32 v130, 18, v30
	v_add_u32_e32 v129, 3, v30
	v_add_u32_e32 v128, 19, v30
	v_cvt_pk_bf16_f32 v28, v110, v111
	v_cvt_pk_bf16_f32 v29, v112, v113
	v_mad_i64_i32 v[40:41], s[4:5], v30, s27, v[152:153]
	v_cvt_pk_bf16_f32 v30, v106, v107
	v_cvt_pk_bf16_f32 v31, v108, v109
	ds_read2st64_b32 v[10:11], v190 offset0:59 offset1:60
	ds_read2st64_b32 v[20:21], v189 offset0:57 offset1:58
	v_mfma_f32_16x16x32_bf16 v[16:19], v[28:31], v[70:73], v[2:5]
	s_nop 2
	ds_read2st64_b32 v[2:3], v188 offset0:55 offset1:56
	ds_read2st64_b32 v[4:5], v187 offset0:53 offset1:54
	v_mad_i64_i32 v[124:125], s[4:5], v134, s27, v[150:151]
	v_mad_i64_i32 v[122:123], s[4:5], v133, s27, v[150:151]
	v_mad_i64_i32 v[120:121], s[4:5], v132, s27, v[150:151]
	v_mad_i64_i32 v[116:117], s[4:5], v131, s27, v[150:151]
	v_mad_i64_i32 v[114:115], s[4:5], v130, s27, v[150:151]
	v_mad_i64_i32 v[112:113], s[4:5], v129, s27, v[150:151]
	v_mad_i64_i32 v[110:111], s[4:5], v128, s27, v[150:151]
	v_mad_i64_i32 v[118:119], s[4:5], v134, s27, v[152:153]
	v_add_u32_e32 v176, 0x100, v176
	v_lshl_add_u64 v[156:157], v[156:157], 0, s[62:63]
	s_waitcnt vmcnt(1)
	v_mul_f32_e32 v23, v171, v248
	v_mul_f32_e32 v24, v170, v248
	s_waitcnt vmcnt(0)
	v_fma_f32 v23, v170, v249, -v23
	v_fmac_f32_e32 v24, v171, v249
	s_waitcnt lgkmcnt(5)
	v_add_f32_e32 v22, v23, v6
	v_add_f32_e32 v23, v24, v7
	v_mul_f32_e32 v24, v171, v23
	ds_write2st64_b32 v192, v22, v23 offset0:63 offset1:64
	v_mul_f32_e32 v23, v170, v23
	v_fmac_f32_e32 v23, v171, v22
	v_fma_f32 v24, v170, v22, -v24
	s_waitcnt lgkmcnt(5)
	v_add_f32_e32 v23, v9, v23
	v_add_f32_e32 v22, v8, v24
	v_mul_f32_e32 v24, v171, v23
	ds_write2st64_b32 v191, v22, v23 offset0:61 offset1:62
	v_fma_f32 v24, v170, v22, -v24
	v_mul_f32_e32 v22, v171, v22
	v_fmac_f32_e32 v22, v170, v23
	s_waitcnt lgkmcnt(5)
	v_add_f32_e32 v22, v11, v22
	v_add_f32_e32 v23, v10, v24
	v_mul_f32_e32 v24, v171, v22
	ds_write2st64_b32 v190, v23, v22 offset0:59 offset1:60
	v_fma_f32 v24, v170, v23, -v24
	v_mul_f32_e32 v23, v171, v23
	v_fmac_f32_e32 v23, v170, v22
	s_waitcnt lgkmcnt(5)
	v_add_f32_e32 v23, v21, v23
	v_add_f32_e32 v22, v20, v24
	v_mul_f32_e32 v24, v171, v23
	ds_write2st64_b32 v189, v22, v23 offset0:57 offset1:58
	v_fma_f32 v24, v170, v22, -v24
	v_mul_f32_e32 v22, v171, v22
	v_fmac_f32_e32 v22, v170, v23
	s_waitcnt lgkmcnt(5)
	v_add_f32_e32 v22, v3, v22
	v_add_f32_e32 v23, v2, v24
	v_mul_f32_e32 v24, v171, v22
	ds_write2st64_b32 v188, v23, v22 offset0:55 offset1:56
	v_fma_f32 v24, v170, v23, -v24
	v_mul_f32_e32 v23, v171, v23
	ds_read2st64_b32 v[6:7], v186 offset0:51 offset1:52
	v_fmac_f32_e32 v23, v170, v22
	s_waitcnt lgkmcnt(6)
	v_add_f32_e32 v23, v5, v23
	v_add_f32_e32 v22, v4, v24
	v_mul_f32_e32 v24, v171, v23
	ds_write2st64_b32 v187, v22, v23 offset0:53 offset1:54
	v_fma_f32 v24, v170, v22, -v24
	v_mul_f32_e32 v22, v171, v22
	ds_read2st64_b32 v[8:9], v184 offset0:49 offset1:50
	v_fmac_f32_e32 v22, v170, v23
	s_waitcnt lgkmcnt(2)
	v_add_f32_e32 v22, v7, v22
	v_add_f32_e32 v23, v6, v24
	v_mul_f32_e32 v24, v171, v22
	ds_write2st64_b32 v186, v23, v22 offset0:51 offset1:52
	v_fma_f32 v24, v170, v23, -v24
	v_mul_f32_e32 v23, v171, v23
	ds_read2st64_b32 v[10:11], v183 offset0:47 offset1:48
	v_fmac_f32_e32 v23, v170, v22
	s_waitcnt lgkmcnt(2)
	v_add_f32_e32 v23, v9, v23
	v_add_f32_e32 v22, v8, v24
	v_mul_f32_e32 v24, v171, v23
	ds_write2st64_b32 v184, v22, v23 offset0:49 offset1:50
	v_fma_f32 v24, v170, v22, -v24
	v_mul_f32_e32 v22, v171, v22
	ds_read2st64_b32 v[20:21], v182 offset0:45 offset1:46
	v_fmac_f32_e32 v22, v170, v23
	s_waitcnt lgkmcnt(2)
	v_add_f32_e32 v22, v11, v22
	v_add_f32_e32 v23, v10, v24
	v_mul_f32_e32 v24, v171, v22
	ds_write2st64_b32 v183, v23, v22 offset0:47 offset1:48
	v_fma_f32 v24, v170, v23, -v24
	v_mul_f32_e32 v23, v171, v23
	ds_read2st64_b32 v[2:3], v181 offset0:43 offset1:44
	v_fmac_f32_e32 v23, v170, v22
	s_waitcnt lgkmcnt(2)
	v_add_f32_e32 v23, v21, v23
	v_add_f32_e32 v22, v20, v24
	v_mul_f32_e32 v24, v171, v23
	ds_write2st64_b32 v182, v22, v23 offset0:45 offset1:46
	v_fma_f32 v24, v170, v22, -v24
	v_mul_f32_e32 v22, v171, v22
	ds_read2st64_b32 v[4:5], v179 offset0:41 offset1:42
	v_fmac_f32_e32 v22, v170, v23
	s_waitcnt lgkmcnt(2)
	v_add_f32_e32 v22, v3, v22
	v_add_f32_e32 v23, v2, v24
	v_mul_f32_e32 v24, v171, v22
	ds_write2st64_b32 v181, v23, v22 offset0:43 offset1:44
	v_fma_f32 v24, v170, v23, -v24
	v_mul_f32_e32 v23, v171, v23
	ds_read2st64_b32 v[6:7], v178 offset0:39 offset1:40
	v_fmac_f32_e32 v23, v170, v22
	s_waitcnt lgkmcnt(2)
; template <bool PHASE_C>
; DEVI void phase_s5(const Params& p, char* lds) {
;     ...
;       float bur[32], bui[32];
; #pragma unroll
;       for (int s = 0; s < 32; ++s) { bur[s] = wl[s * 132 + lane]; bui[s] = wl[s * 132 + 64 + lane]; }
; #pragma unroll
;       for (int s = 0; s < 32; ++s) {
;         const int t = d ? 31 - s : s;
;         const float nr = ar * hr - ai * him + bur[t];
;         const float ni = ar * him + ai * hr + bui[t];
;         hr = nr; him = ni;
;         if (PHASE_C) { bur[t] = hr; bui[t] = him; }
;       }
	v_add_f32_e32 v23, v5, v23
	v_add_f32_e32 v22, v4, v24
	v_mul_f32_e32 v24, v171, v23
	ds_write2st64_b32 v179, v22, v23 offset0:41 offset1:42
	v_fma_f32 v24, v170, v22, -v24
	v_mul_f32_e32 v22, v171, v22
	ds_read2st64_b32 v[8:9], v177 offset0:37 offset1:38
	ds_read2st64_b32 v[4:5], v177 offset0:4 offset1:5
	v_fmac_f32_e32 v22, v170, v23
	s_waitcnt lgkmcnt(3)
	v_add_f32_e32 v22, v7, v22
	v_add_f32_e32 v23, v6, v24
	v_mul_f32_e32 v24, v171, v22
	ds_write2st64_b32 v178, v23, v22 offset0:39 offset1:40
	v_fma_f32 v24, v170, v23, -v24
	v_mul_f32_e32 v23, v171, v23
	ds_read2st64_b32 v[10:11], v193 offset0:35 offset1:36
	v_fmac_f32_e32 v23, v170, v22
	s_waitcnt lgkmcnt(3)
	v_add_f32_e32 v23, v9, v23
	v_add_f32_e32 v22, v8, v24
	v_mul_f32_e32 v24, v171, v23
	ds_read2st64_b32 v[20:21], v163 offset0:33 offset1:34
	ds_write2st64_b32 v177, v22, v23 offset0:37 offset1:38
	v_fma_f32 v24, v170, v22, -v24
	v_mul_f32_e32 v22, v171, v22
	v_fmac_f32_e32 v22, v170, v23
	s_waitcnt lgkmcnt(2)
	v_add_f32_e32 v22, v11, v22
	ds_read2st64_b32 v[2:3], v192 offset0:30 offset1:31
	v_add_f32_e32 v23, v10, v24
	v_mul_f32_e32 v24, v171, v22
	v_mul_f32_e32 v25, v171, v23
	v_fma_f32 v24, v170, v23, -v24
	v_fmac_f32_e32 v25, v170, v22
	s_waitcnt lgkmcnt(2)
	v_add_f32_e32 v20, v20, v24
	ds_read2st64_b32 v[6:7], v191 offset0:28 offset1:29
	v_add_f32_e32 v21, v21, v25
	v_mul_f32_e32 v25, v171, v20
	v_mul_f32_e32 v24, v171, v21
	v_fmac_f32_e32 v25, v170, v21
	v_fma_f32 v24, v170, v20, -v24
	s_waitcnt lgkmcnt(1)
	v_add_f32_e32 v25, v3, v25
	ds_read2st64_b32 v[8:9], v190 offset0:26 offset1:27
	v_add_f32_e32 v24, v2, v24
	v_mul_f32_e32 v26, v171, v25
	ds_write2st64_b32 v192, v24, v25 offset0:30 offset1:31
	v_fma_f32 v26, v170, v24, -v26
	v_mul_f32_e32 v24, v171, v24
	v_fmac_f32_e32 v24, v170, v25
	s_waitcnt lgkmcnt(2)
	v_add_f32_e32 v25, v6, v26
	ds_write2st64_b32 v193, v23, v22 offset0:35 offset1:36
	ds_read2st64_b32 v[22:23], v189 offset0:24 offset1:25
	v_add_f32_e32 v24, v7, v24
	v_mul_f32_e32 v27, v171, v25
	v_mul_f32_e32 v26, v171, v24
	v_fmac_f32_e32 v27, v170, v24
	v_fma_f32 v26, v170, v25, -v26
	s_waitcnt lgkmcnt(3)
	v_add_f32_e32 v27, v9, v27
	ds_write2st64_b32 v163, v20, v21 offset0:33 offset1:34
	ds_read2st64_b32 v[20:21], v188 offset0:22 offset1:23
	v_add_f32_e32 v26, v8, v26
	v_mul_f32_e32 v28, v171, v27
	ds_write2st64_b32 v190, v26, v27 offset0:26 offset1:27
	v_fma_f32 v28, v170, v26, -v28
	v_mul_f32_e32 v26, v171, v26
	v_fmac_f32_e32 v26, v170, v27
	s_waitcnt lgkmcnt(3)
	v_add_f32_e32 v27, v22, v28
	v_add_f32_e32 v26, v23, v26
	v_mul_f32_e32 v29, v171, v27
	ds_read2st64_b32 v[6:7], v187 offset0:20 offset1:21
	v_mul_f32_e32 v28, v171, v26
	v_fmac_f32_e32 v29, v170, v26
	v_fma_f32 v28, v170, v27, -v28
	s_waitcnt lgkmcnt(2)
	v_add_f32_e32 v29, v21, v29
	v_add_f32_e32 v28, v20, v28
	v_mul_f32_e32 v30, v171, v29
	ds_write2st64_b32 v191, v25, v24 offset0:28 offset1:29
	ds_read2st64_b32 v[24:25], v186 offset0:18 offset1:19
	ds_write2st64_b32 v188, v28, v29 offset0:22 offset1:23
	v_fma_f32 v30, v170, v28, -v30
	v_mul_f32_e32 v28, v171, v28
	v_fmac_f32_e32 v28, v170, v29
	s_waitcnt lgkmcnt(3)
	v_add_f32_e32 v29, v6, v30
	v_add_f32_e32 v28, v7, v28
	ds_read2st64_b32 v[22:23], v184 offset0:16 offset1:17
	v_mul_f32_e32 v30, v171, v28
	v_mul_f32_e32 v31, v171, v29
	ds_write2st64_b32 v187, v29, v28 offset0:20 offset1:21
	v_fma_f32 v29, v170, v29, -v30
	v_fmac_f32_e32 v31, v170, v28
	s_waitcnt lgkmcnt(3)
	v_add_f32_e32 v24, v24, v29
	v_add_f32_e32 v25, v25, v31
	ds_write2st64_b32 v189, v27, v26 offset0:24 offset1:25
	ds_read2st64_b32 v[26:27], v183 offset0:14 offset1:15
	v_mul_f32_e32 v28, v171, v25
	v_mul_f32_e32 v29, v171, v24
	ds_write2st64_b32 v186, v24, v25 offset0:18 offset1:19
	v_fma_f32 v24, v170, v24, -v28
	v_fmac_f32_e32 v29, v170, v25
	s_waitcnt lgkmcnt(4)
	v_add_f32_e32 v22, v22, v24
	v_add_f32_e32 v23, v23, v29
	ds_read2st64_b32 v[20:21], v182 offset0:12 offset1:13
	v_mul_f32_e32 v24, v171, v23
	v_mul_f32_e32 v25, v171, v22
	ds_write2st64_b32 v184, v22, v23 offset0:16 offset1:17
	v_fma_f32 v22, v170, v22, -v24
	v_fmac_f32_e32 v25, v170, v23
	s_waitcnt lgkmcnt(3)
	v_add_f32_e32 v22, v26, v22
	v_add_f32_e32 v23, v27, v25
	ds_read2st64_b32 v[8:9], v181 offset0:10 offset1:11
	v_mul_f32_e32 v24, v171, v23
	v_mul_f32_e32 v25, v171, v22
	ds_write2st64_b32 v183, v22, v23 offset0:14 offset1:15
	v_fma_f32 v22, v170, v22, -v24
	v_fmac_f32_e32 v25, v170, v23
	s_waitcnt lgkmcnt(3)
	v_add_f32_e32 v20, v20, v22
	v_add_f32_e32 v21, v21, v25
	ds_read2st64_b32 v[2:3], v179 offset0:8 offset1:9
	v_mul_f32_e32 v22, v171, v21
	v_mul_f32_e32 v23, v171, v20
	ds_write2st64_b32 v182, v20, v21 offset0:12 offset1:13
	v_fma_f32 v20, v170, v20, -v22
	v_fmac_f32_e32 v23, v170, v21
	s_waitcnt lgkmcnt(3)
	v_add_f32_e32 v8, v8, v20
	v_add_f32_e32 v9, v9, v23
	ds_read2st64_b32 v[10:11], v178 offset0:6 offset1:7
	v_mul_f32_e32 v20, v171, v9
	v_mul_f32_e32 v21, v171, v8
	ds_write2st64_b32 v181, v8, v9 offset0:10 offset1:11
	v_fma_f32 v8, v170, v8, -v20
	v_fmac_f32_e32 v21, v170, v9
	s_waitcnt lgkmcnt(3)
	v_add_f32_e32 v2, v2, v8
	v_add_f32_e32 v3, v3, v21
	v_mul_f32_e32 v8, v171, v3
	v_mul_f32_e32 v9, v171, v2
	ds_write2st64_b32 v179, v2, v3 offset0:8 offset1:9
	v_fma_f32 v2, v170, v2, -v8
	v_fmac_f32_e32 v9, v170, v3
	s_waitcnt lgkmcnt(2)
	v_add_f32_e32 v2, v10, v2
	v_add_f32_e32 v3, v11, v9
	ds_read2_b32 v[6:7], v163 offset0:132 offset1:196
	v_mul_f32_e32 v8, v171, v3
	v_mul_f32_e32 v9, v171, v2
	ds_write2st64_b32 v178, v2, v3 offset0:6 offset1:7
	v_fma_f32 v2, v170, v2, -v8
	v_fmac_f32_e32 v9, v170, v3
	v_add_f32_e32 v2, v4, v2
	v_add_f32_e32 v3, v5, v9
	v_mul_f32_e32 v4, v171, v3
	v_mul_f32_e32 v5, v171, v2
	ds_write2st64_b32 v177, v2, v3 offset0:4 offset1:5
	v_fma_f32 v2, v170, v2, -v4
	v_fmac_f32_e32 v5, v170, v3
	s_waitcnt lgkmcnt(2)
; DEVI unsigned cvtpk(float lo, float hi) { unsigned r; asm("v_cvt_pk_bf16_f32 %0, %1, %2" : "=v"(r) : "v"(lo), "v"(hi)); return r; }
; DEVI bf16_t f2bf(float x) { return (bf16_t)(cvtpk(x, 0.f) & 0xffffu); }
; DEVI float bf2f(bf16_t b) { return __uint_as_float(((unsigned)b) << 16); }
; template <bool PHASE_C>
; DEVI void phase_s5(const Params& p, char* lds) {
;     ...
;       if (PHASE_C) {
;         asm volatile("s_waitcnt lgkmcnt(0)" ::: "memory");
; #pragma unroll
;         for (int ks = 0; ks < 4; ++ks) {
;           const bf16x8 cf = cm[d][ks];
;           const float* a0p = wl + (lane & 15) * 132 + ks * 32 + (lane >> 4) * 8;
;           const f32x4 a00 = *(const f32x4*)a0p, a01 = *(const f32x4*)(a0p + 4);
;           const f32x4 a10 = *(const f32x4*)(a0p + 16 * 132), a11 = *(const f32x4*)(a0p + 16 * 132 + 4);
;           u32x4 w0 = {cvtpk(a00[0], a00[1]), cvtpk(a00[2], a00[3]), cvtpk(a01[0], a01[1]), cvtpk(a01[2], a01[3])};
;           u32x4 w1 = {cvtpk(a10[0], a10[1]), cvtpk(a10[2], a10[3]), cvtpk(a11[0], a11[1]), cvtpk(a11[2], a11[3])};
;           y0 = __builtin_amdgcn_mfma_f32_16x16x32_bf16(*(bf16x8*)&w0, cf, y0, 0, 0, 0);
;           y1 = __builtin_amdgcn_mfma_f32_16x16x32_bf16(*(bf16x8*)&w1, cf, y1, 0, 0, 0);
;         }
;         asm volatile("s_waitcnt lgkmcnt(0)" ::: "memory");
;       }
;     }
;     if (PHASE_C) {
;       const int c = lane & 15, ch = g * 16 + c;
;       float u0[4], u1[4];
; #pragma unroll
;       for (int r = 0; r < 4; ++r) {
;         const int t0 = (lane >> 4) * 4 + r;
;         u0[r] = bf2f(U[(size_t)(tok0 + t0) * LDP + ch]); u1[r] = bf2f(U[(size_t)(tok0 + 16 + t0) * LDP + ch]);
;       }
; #pragma unroll
;       for (int r = 0; r < 4; ++r) {
;         const int t0 = (lane >> 4) * 4 + r;
;         Z[(size_t)(tok0 + t0) * LDP + ch] = f2bf(gelu_tanh(y0[r] + dsk * u0[r]));
;         Z[(size_t)(tok0 + 16 + t0) * LDP + ch] = f2bf(gelu_tanh(y1[r] + dsk * u1[r]));
	v_add_f32_e32 v2, v6, v2
	v_add_f32_e32 v3, v7, v5
	v_mul_f32_e32 v4, v171, v3
	v_mul_f32_e32 v5, v171, v2
	ds_write2_b32 v163, v2, v3 offset0:132 offset1:196
	v_fma_f32 v2, v170, v2, -v4
	v_fmac_f32_e32 v5, v170, v3
	v_add_f32_e32 v0, v0, v2
	v_add_f32_e32 v1, v1, v5
	ds_write2st64_b32 v163, v0, v1 offset1:1
	s_waitcnt lgkmcnt(0)
	ds_read_b128 v[0:3], v165
	ds_read_b128 v[4:7], v165 offset:16
	ds_read_b128 v[8:11], v165 offset:8448
	ds_read_b128 v[20:23], v165 offset:8464
	ds_read_b128 v[24:27], v165 offset:128
	ds_read_b128 v[28:31], v165 offset:144
	ds_read_b128 v[32:35], v165 offset:8576
	s_waitcnt lgkmcnt(6)
	v_cvt_pk_bf16_f32 v36, v0, v1
	v_cvt_pk_bf16_f32 v37, v2, v3
	s_waitcnt lgkmcnt(5)
	v_cvt_pk_bf16_f32 v38, v4, v5
	v_cvt_pk_bf16_f32 v39, v6, v7
	s_waitcnt lgkmcnt(3)
	v_cvt_pk_bf16_f32 v180, v20, v21
	v_cvt_pk_bf16_f32 v181, v22, v23
	s_waitcnt lgkmcnt(2)
	v_cvt_pk_bf16_f32 v20, v24, v25
	v_cvt_pk_bf16_f32 v21, v26, v27
	s_waitcnt lgkmcnt(1)
	v_cvt_pk_bf16_f32 v22, v28, v29
	v_mfma_f32_16x16x32_bf16 v[36:39], v[36:39], v[82:85], v[12:15]
	v_cvt_pk_bf16_f32 v23, v30, v31
	ds_read_b128 v[106:109], v165 offset:8592
	ds_read_b128 v[0:3], v165 offset:8704
	v_cvt_pk_bf16_f32 v178, v8, v9
	v_cvt_pk_bf16_f32 v179, v10, v11
	ds_read_b128 v[182:185], v165 offset:256
	ds_read_b128 v[186:189], v165 offset:272
	s_waitcnt lgkmcnt(4)
	v_cvt_pk_bf16_f32 v8, v32, v33
	v_cvt_pk_bf16_f32 v9, v34, v35
	ds_read_b128 v[4:7], v165 offset:8720
	ds_read_b128 v[24:27], v165 offset:384
	ds_read_b128 v[12:15], v165 offset:400
	v_mfma_f32_16x16x32_bf16 v[32:35], v[178:181], v[82:85], v[16:19]
	s_waitcnt lgkmcnt(6)
	v_cvt_pk_bf16_f32 v10, v106, v107
	v_cvt_pk_bf16_f32 v11, v108, v109
	s_waitcnt lgkmcnt(4)
	v_cvt_pk_bf16_f32 v28, v182, v183
	v_mfma_f32_16x16x32_bf16 v[36:39], v[20:23], v[90:93], v[36:39]
	ds_read_b128 v[20:23], v165 offset:8848
	ds_read_b128 v[16:19], v165 offset:8832
	s_waitcnt lgkmcnt(0)
	global_load_ushort v126, v[126:127], off
	v_mfma_f32_16x16x32_bf16 v[8:11], v[8:11], v[90:93], v[32:35]
	global_load_ushort v124, v[124:125], off
	v_cvt_pk_bf16_f32 v29, v184, v185
	global_load_ushort v122, v[122:123], off
	s_waitcnt lgkmcnt(5)
	v_cvt_pk_bf16_f32 v30, v186, v187
	global_load_ushort v125, v[116:117], off
	global_load_ushort v123, v[120:121], off
	global_load_ushort v127, v[114:115], off
	v_mad_i64_i32 v[114:115], s[4:5], v129, s27, v[152:153]
	global_load_ushort v129, v[112:113], off
	v_cvt_pk_bf16_f32 v31, v188, v189
	global_load_ushort v110, v[110:111], off
	v_cvt_pk_bf16_f32 v0, v0, v1
	v_cvt_pk_bf16_f32 v1, v2, v3
	s_waitcnt lgkmcnt(4)
	v_cvt_pk_bf16_f32 v2, v4, v5
	v_mfma_f32_16x16x32_bf16 v[28:31], v[28:31], v[98:101], v[36:39]
	v_cvt_pk_bf16_f32 v3, v6, v7
	s_waitcnt lgkmcnt(3)
	v_cvt_pk_bf16_f32 v4, v24, v25
	v_cvt_pk_bf16_f32 v5, v26, v27
	s_waitcnt lgkmcnt(2)
	v_cvt_pk_bf16_f32 v6, v12, v13
	v_cvt_pk_bf16_f32 v7, v14, v15
	v_mad_i64_i32 v[112:113], s[4:5], v128, s27, v[152:153]
	v_mfma_f32_16x16x32_bf16 v[0:3], v[0:3], v[98:101], v[8:11]
	s_waitcnt lgkmcnt(0)
	v_cvt_pk_bf16_f32 v8, v16, v17
	v_cvt_pk_bf16_f32 v9, v18, v19
	v_cvt_pk_bf16_f32 v10, v20, v21
	v_mfma_f32_16x16x32_bf16 v[4:7], v[4:7], v[102:105], v[28:31]
	v_cvt_pk_bf16_f32 v11, v22, v23
	v_mad_i64_i32 v[108:109], s[4:5], v133, s27, v[152:153]
	v_mfma_f32_16x16x32_bf16 v[0:3], v[8:11], v[102:105], v[0:3]
	v_mad_i64_i32 v[106:107], s[4:5], v132, s27, v[152:153]
	v_mad_i64_i32 v[120:121], s[4:5], v131, s27, v[152:153]
	v_mad_i64_i32 v[116:117], s[4:5], v130, s27, v[152:153]
	s_waitcnt vmcnt(7)
	v_lshlrev_b32_e32 v8, 16, v126
	s_nop 0
	v_fma_f32 v4, v172, v8, v4
	s_waitcnt vmcnt(6)
	v_lshlrev_b32_e32 v9, 16, v124
	v_fma_f32 v0, v172, v9, v0
	s_waitcnt vmcnt(5)
	v_lshlrev_b32_e32 v10, 16, v122
	v_mul_f32_e32 v8, 0x3d372713, v4
	v_fma_f32 v5, v172, v10, v5
	v_mul_f32_e32 v10, 0x3d372713, v0
	v_mul_f32_e32 v8, v4, v8
	s_waitcnt vmcnt(3)
	v_lshlrev_b32_e32 v11, 16, v123
	v_mul_f32_e32 v9, 0.5, v4
	v_mul_f32_e32 v10, v0, v10
	v_fma_f32 v4, v4, v8, v4
	v_lshlrev_b32_e32 v12, 16, v125
	v_fma_f32 v1, v172, v11, v1
	v_mul_f32_e32 v11, 0x3d372713, v5
	v_mul_f32_e32 v19, 0.5, v0
	v_fma_f32 v0, v0, v10, v0
	v_mul_f32_e32 v4, 0x3f4c422a, v4
	s_waitcnt vmcnt(2)
	v_lshlrev_b32_e32 v13, 16, v127
	v_fma_f32 v6, v172, v12, v6
	v_mul_f32_e32 v12, 0x3d372713, v1
	v_mul_f32_e32 v11, v5, v11
	v_mul_f32_e32 v0, 0x3f4c422a, v0
	v_add_f32_e32 v4, v4, v4
	s_waitcnt vmcnt(1)
	v_lshlrev_b32_e32 v14, 16, v129
	v_fma_f32 v2, v172, v13, v2
	v_mul_f32_e32 v13, 0x3d372713, v6
	v_mul_f32_e32 v20, 0.5, v5
	v_mul_f32_e32 v12, v1, v12
	v_fma_f32 v5, v5, v11, v5
	v_add_f32_e32 v0, v0, v0
	v_mul_f32_e32 v4, 0x3fb8aa3b, v4
	s_waitcnt vmcnt(0)
; DEVI bf16_t f2bf(float x) { return (bf16_t)(cvtpk(x, 0.f) & 0xffffu); }
; DEVI float bf2f(bf16_t b) { return __uint_as_float(((unsigned)b) << 16); }
; DEVI float gelu_tanh(float x) {
;   float u = 0.7978845608028654f * (x + 0.044715f * x * x * x);
;   float t = 1.f - 2.f / (1.f + __expf(2.f * u));
;   return 0.5f * x * (1.f + t);
; }
; template <bool PHASE_C>
; DEVI void phase_s5(const Params& p, char* lds) {
;     ...
;     if (PHASE_C) {
;       const int c = lane & 15, ch = g * 16 + c;
;       float u0[4], u1[4];
; #pragma unroll
;       for (int r = 0; r < 4; ++r) {
;         const int t0 = (lane >> 4) * 4 + r;
;         u0[r] = bf2f(U[(size_t)(tok0 + t0) * LDP + ch]); u1[r] = bf2f(U[(size_t)(tok0 + 16 + t0) * LDP + ch]);
;       }
; #pragma unroll
;       for (int r = 0; r < 4; ++r) {
;         const int t0 = (lane >> 4) * 4 + r;
;         Z[(size_t)(tok0 + t0) * LDP + ch] = f2bf(gelu_tanh(y0[r] + dsk * u0[r]));
;         Z[(size_t)(tok0 + 16 + t0) * LDP + ch] = f2bf(gelu_tanh(y1[r] + dsk * u1[r]));
;       }
;     }
;    }
;   }
	v_lshlrev_b32_e32 v15, 16, v110
	v_fmac_f32_e32 v7, v172, v14
	v_mul_f32_e32 v14, 0x3d372713, v2
	v_mul_f32_e32 v21, 0.5, v1
	v_mul_f32_e32 v13, v6, v13
	v_fma_f32 v1, v1, v12, v1
	v_mul_f32_e32 v5, 0x3f4c422a, v5
	v_mul_f32_e32 v0, 0x3fb8aa3b, v0
	v_exp_f32_e32 v4, v4
	v_fmac_f32_e32 v3, v172, v15
	v_mul_f32_e32 v15, 0x3d372713, v7
	v_mul_f32_e32 v22, 0.5, v6
	v_mul_f32_e32 v14, v2, v14
	v_fma_f32 v6, v6, v13, v6
	v_mul_f32_e32 v1, 0x3f4c422a, v1
	v_add_f32_e32 v5, v5, v5
	v_exp_f32_e32 v0, v0
	v_mul_f32_e32 v17, 0x3d372713, v3
	v_mul_f32_e32 v23, 0.5, v2
	v_mul_f32_e32 v15, v7, v15
	v_fma_f32 v2, v2, v14, v2
	v_mul_f32_e32 v6, 0x3f4c422a, v6
	v_add_f32_e32 v1, v1, v1
	v_mul_f32_e32 v5, 0x3fb8aa3b, v5
	v_mul_f32_e32 v16, 0.5, v7
	v_mul_f32_e32 v17, v3, v17
	v_fma_f32 v7, v7, v15, v7
	v_mul_f32_e32 v2, 0x3f4c422a, v2
	v_add_f32_e32 v6, v6, v6
	v_mul_f32_e32 v1, 0x3fb8aa3b, v1
	v_exp_f32_e32 v5, v5
	v_mul_f32_e32 v18, 0.5, v3
	v_fma_f32 v3, v3, v17, v3
	v_mul_f32_e32 v7, 0x3f4c422a, v7
	v_add_f32_e32 v2, v2, v2
	v_mul_f32_e32 v6, 0x3fb8aa3b, v6
	v_exp_f32_e32 v1, v1
	v_add_f32_e32 v4, 1.0, v4
	v_mul_f32_e32 v3, 0x3f4c422a, v3
	v_add_f32_e32 v7, v7, v7
	v_mul_f32_e32 v2, 0x3fb8aa3b, v2
	v_exp_f32_e32 v6, v6
	v_add_f32_e32 v0, 1.0, v0
	v_div_scale_f32 v8, s[4:5], v4, v4, 2.0
	v_add_f32_e32 v3, v3, v3
	v_mul_f32_e32 v7, 0x3fb8aa3b, v7
	v_exp_f32_e32 v2, v2
	v_div_scale_f32 v11, s[4:5], v0, v0, 2.0
	v_rcp_f32_e32 v32, v8
	v_mul_f32_e32 v3, 0x3fb8aa3b, v3
	v_exp_f32_e32 v7, v7
	v_add_f32_e32 v5, 1.0, v5
	v_rcp_f32_e32 v33, v11
	v_exp_f32_e32 v3, v3
	v_add_f32_e32 v1, 1.0, v1
	v_div_scale_f32 v13, s[4:5], v5, v5, 2.0
	v_add_f32_e32 v6, 1.0, v6
	v_div_scale_f32 v15, s[4:5], v1, v1, 2.0
	v_rcp_f32_e32 v34, v13
	v_add_f32_e32 v2, 1.0, v2
	v_div_scale_f32 v17, s[4:5], v6, v6, 2.0
	v_rcp_f32_e32 v35, v15
	v_fma_f32 v110, -v8, v32, 1.0
	v_add_f32_e32 v7, 1.0, v7
	v_div_scale_f32 v10, vcc, 2.0, v4, 2.0
	v_div_scale_f32 v24, s[4:5], v2, v2, 2.0
	v_rcp_f32_e32 v36, v17
	v_fma_f32 v111, -v11, v33, 1.0
	v_fmac_f32_e32 v32, v110, v32
	v_add_f32_e32 v3, 1.0, v3
	v_div_scale_f32 v12, s[8:9], 2.0, v0, 2.0
	v_div_scale_f32 v28, s[4:5], v7, v7, 2.0
	v_rcp_f32_e32 v37, v24
	v_fmac_f32_e32 v33, v111, v33
	v_mul_f32_e32 v110, v10, v32
	v_div_scale_f32 v30, s[4:5], v3, v3, 2.0
	v_rcp_f32_e32 v38, v28
	v_fma_f32 v122, -v13, v34, 1.0
	v_mul_f32_e32 v111, v12, v33
	v_fma_f32 v128, -v8, v110, v10
	v_div_scale_f32 v14, s[10:11], 2.0, v5, 2.0
	v_rcp_f32_e32 v39, v30
	v_fma_f32 v123, -v15, v35, 1.0
	v_fmac_f32_e32 v34, v122, v34
	v_fmac_f32_e32 v110, v128, v32
	v_fma_f32 v128, -v11, v111, v12
	v_div_scale_f32 v25, s[12:13], 2.0, v1, 2.0
	v_fma_f32 v124, -v17, v36, 1.0
	v_fmac_f32_e32 v35, v123, v35
	v_mul_f32_e32 v122, v14, v34
	v_fmac_f32_e32 v111, v128, v33
	v_fma_f32 v8, -v8, v110, v10
	v_div_scale_f32 v26, s[16:17], 2.0, v6, 2.0
	v_fma_f32 v125, -v24, v37, 1.0
	v_fmac_f32_e32 v36, v124, v36
	v_mul_f32_e32 v123, v25, v35
	v_fma_f32 v128, -v13, v122, v14
	v_fma_f32 v10, -v11, v111, v12
	v_div_fmas_f32 v8, v8, v32, v110
	s_mov_b64 vcc, s[8:9]
	v_div_scale_f32 v27, s[18:19], 2.0, v2, 2.0
	v_fma_f32 v126, -v28, v38, 1.0
	v_fmac_f32_e32 v37, v125, v37
	v_mul_f32_e32 v124, v26, v36
	v_fmac_f32_e32 v122, v128, v34
	v_fma_f32 v128, -v15, v123, v25
	v_div_fixup_f32 v4, v8, v4, 2.0
	v_div_fmas_f32 v8, v10, v33, v111
	v_div_scale_f32 v29, s[6:7], 2.0, v7, 2.0
	v_fma_f32 v127, -v30, v39, 1.0
	v_fmac_f32_e32 v38, v126, v38
	v_mul_f32_e32 v125, v27, v37
	v_fmac_f32_e32 v123, v128, v35
	v_fma_f32 v128, -v17, v124, v26
	v_fma_f32 v11, -v13, v122, v14
	s_mov_b64 vcc, s[10:11]
	v_div_fixup_f32 v0, v8, v0, 2.0
	v_div_scale_f32 v31, s[4:5], 2.0, v3, 2.0
	v_fmac_f32_e32 v39, v127, v39
	v_mul_f32_e32 v126, v29, v38
	v_fmac_f32_e32 v124, v128, v36
	v_fma_f32 v128, -v24, v125, v27
	v_fma_f32 v12, -v15, v123, v25
	v_sub_f32_e32 v4, 1.0, v4
	v_div_fmas_f32 v10, v11, v34, v122
	s_mov_b64 vcc, s[12:13]
	v_sub_f32_e32 v0, 1.0, v0
	v_mul_f32_e32 v127, v31, v39
	v_fmac_f32_e32 v125, v128, v37
	v_fma_f32 v128, -v28, v126, v29
	v_fma_f32 v13, -v17, v124, v26
	v_add_f32_e32 v4, 1.0, v4
	v_div_fmas_f32 v8, v12, v35, v123
	v_div_fixup_f32 v5, v10, v5, 2.0
	s_mov_b64 vcc, s[16:17]
	v_add_f32_e32 v0, 1.0, v0
	v_fmac_f32_e32 v126, v128, v38
	v_fma_f32 v128, -v30, v127, v31
	v_fma_f32 v14, -v24, v125, v27
	v_mul_f32_e32 v4, v9, v4
	v_div_fmas_f32 v9, v13, v36, v124
	v_div_fixup_f32 v1, v8, v1, 2.0
	v_sub_f32_e32 v5, 1.0, v5
	s_mov_b64 vcc, s[18:19]
	v_mul_f32_e32 v0, v19, v0
	v_fmac_f32_e32 v127, v128, v39
	v_fma_f32 v15, -v28, v126, v29
	v_cvt_pk_bf16_f32 v4, v4, v139
	v_div_fmas_f32 v8, v14, v37, v125
	v_div_fixup_f32 v6, v9, v6, 2.0
	v_add_f32_e32 v5, 1.0, v5
	v_sub_f32_e32 v1, 1.0, v1
	v_cvt_pk_bf16_f32 v0, v0, v139
	s_mov_b64 vcc, s[6:7]
	v_fma_f32 v17, -v30, v127, v31
	global_store_short v[40:41], v4, off
	v_mul_f32_e32 v4, v20, v5
	v_div_fixup_f32 v2, v8, v2, 2.0
	v_add_f32_e32 v1, 1.0, v1
	v_sub_f32_e32 v5, 1.0, v6
	v_div_fmas_f32 v6, v15, v38, v126
	global_store_short v[118:119], v0, off
	v_cvt_pk_bf16_f32 v0, v4, v139
	s_mov_b64 vcc, s[4:5]
	v_mul_f32_e32 v1, v21, v1
	v_add_f32_e32 v4, 1.0, v5
	v_sub_f32_e32 v2, 1.0, v2
	v_div_fixup_f32 v5, v6, v7, 2.0
	v_div_fmas_f32 v6, v17, v39, v127
	global_store_short v[108:109], v0, off
	v_cvt_pk_bf16_f32 v0, v1, v139
	v_mul_f32_e32 v1, v22, v4
	v_add_f32_e32 v2, 1.0, v2
	v_sub_f32_e32 v4, 1.0, v5
	v_div_fixup_f32 v3, v6, v3, 2.0
	global_store_short v[106:107], v0, off
	v_cvt_pk_bf16_f32 v0, v1, v139
	v_mul_f32_e32 v1, v23, v2
	v_add_f32_e32 v2, 1.0, v4
	v_sub_f32_e32 v3, 1.0, v3
	global_store_short v[120:121], v0, off
	v_cvt_pk_bf16_f32 v0, v1, v139
	v_mul_f32_e32 v1, v16, v2
	v_add_f32_e32 v2, 1.0, v3
	global_store_short v[116:117], v0, off
	v_cvt_pk_bf16_f32 v0, v1, v139
	v_mul_f32_e32 v1, v18, v2
	global_store_short v[114:115], v0, off
	v_cvt_pk_bf16_f32 v0, v1, v139
	global_store_short v[112:113], v0, off
	s_andn2_b64 exec, exec, s[68:69]
	s_cbranch_execnz .LBB0_467
	s_or_b64 exec, exec, s[68:69]
	s_load_dword s2, s[58:59], 0x0
	s_waitcnt lgkmcnt(0)
	v_lshl_add_u32 v159, s2, 2, v159
	v_cmp_lt_i32_e32 vcc, s71, v159
	s_or_b64 s[60:61], vcc, s[60:61]
	s_andn2_b64 exec, exec, s[60:61]
	s_cbranch_execnz .LBB0_466
